# global attn loop: prefetch K/V LDS fragment reads into free VGPRs, counted lgkmcnt waits
# speedup vs baseline: 1.0046x; 1.0046x over previous
; #define MFMA(a, b, c) __builtin_amdgcn_mfma_f32_32x32x16_bf16((a), (b), (c), 0, 0, 0)
; DI int crow(int reg, int h) { return (reg & 3) + 8 * (reg >> 2) + 4 * h; }
; DI float fexp2(float x) { return __builtin_amdgcn_exp2f(x); }
; DI float mx2(float a, float b) { return __builtin_elementwise_maximum(a, b); }
; DI float hmax(float v) { auto rr = __builtin_amdgcn_permlane32_swap(__float_as_uint(v), __float_as_uint(v), false, false); return mx2(__uint_as_float(rr[0]), __uint_as_float(rr[1])); }
; DI f32x16 fzero() { f32x16 z; for (int i = 0; i < 16; ++i) z[i] = 0.f; return z; }
; DI void attn_core2(const u16* __restrict__ P, size_t tokbase, int kcol, int vcol, int n1, int n2, int xs0, bool win, int tq0,
;                    float m0, float l0, const bf16x8 (&qreg)[2][4], f32x16 (&o)[2][2], float (&lsum)[2], char* lds) {
;     ...
;       f32x16 pt[2]; pt[0] = fzero(); pt[1] = fzero();
; #pragma unroll
;       for (int s = 0; s < 4; ++s) {
;         const int ch = 2 * s + h, key = 32 * ks + r;
;         const bf16x8 kf = *(const bf16x8*)(base + ch * 1024 + ((key ^ ch) * 16));
;         pt[0] = MFMA(kf, qreg[0][s], pt[0]);
;         pt[1] = MFMA(kf, qreg[1][s], pt[1]);
;       }
; #pragma unroll
;       for (int qs = 0; qs < 2; ++qs) {
;         if (domask) {
; #pragma unroll
;           for (int reg = 0; reg < 16; ++reg) {
;             const int d = tq0 + 32 * qs - (kt0 + 32 * ks + crow(reg, h));
;             if (d > 128 || d < -128) pt[qs][reg] = -1e30f;
;           }
;         }
;         float mloc = mx2(pt[qs][0], pt[qs][1]);
; #pragma unroll
;         for (int reg = 2; reg < 16; reg += 2) mloc = mx2(mx2(mloc, pt[qs][reg]), pt[qs][reg + 1]);
;         mloc = hmax(mloc) - m[qs];
;         if (__builtin_amdgcn_ballot_w64(mloc > THR) != 0) {
;           const float d = fmaxf(mloc, 0.f);
;           const float alpha = fexp2(-d);
;           m[qs] += d; l[qs] *= alpha; mz[qs] = false;
; #pragma unroll
;           for (int b = 0; b < 2; ++b)
; #pragma unroll
;             for (int reg = 0; reg < 16; ++reg) o[qs][b][reg] *= alpha;
;         }
.LBB0_128:
	v_add_co_u32_e32 v0, vcc, 0xffeeb000, v178
	s_nop 1
	v_addc_co_u32_e32 v1, vcc, -1, v179, vcc
	v_add_co_u32_e32 v2, vcc, 0xfff47000, v178
	global_load_dwordx4 v[162:165], v[0:1], off offset:-2560
	s_nop 0
	v_addc_co_u32_e32 v3, vcc, -1, v179, vcc
	global_load_dwordx4 v[170:173], v[2:3], off offset:-512
	global_load_dwordx4 v[166:169], v[0:1], off offset:-2048
	global_load_dwordx4 v[174:177], v[2:3], off
	ds_read_b128 v[226:229], v187
	ds_read_b128 v[238:241], v188
	ds_read_b128 v[242:245], v189
	ds_read_b128 v[246:249], v214
	s_waitcnt lgkmcnt(3)
	v_mfma_f32_32x32x16_bf16 v[32:47], v[226:229], v[130:133], 0
	v_mfma_f32_32x32x16_bf16 v[16:31], v[226:229], v[146:149], 0
	s_waitcnt lgkmcnt(2)
	v_mfma_f32_32x32x16_bf16 v[32:47], v[238:241], v[134:137], v[32:47]
	v_mfma_f32_32x32x16_bf16 v[16:31], v[238:241], v[150:153], v[16:31]
	s_waitcnt lgkmcnt(1)
	v_mfma_f32_32x32x16_bf16 v[32:47], v[242:245], v[138:141], v[32:47]
	v_mfma_f32_32x32x16_bf16 v[16:31], v[242:245], v[154:157], v[16:31]
	s_waitcnt lgkmcnt(0)
	v_mfma_f32_32x32x16_bf16 v[32:47], v[246:249], v[142:145], v[32:47]
	v_mfma_f32_32x32x16_bf16 v[16:31], v[246:249], v[158:161], v[16:31]
	s_nop 10
	v_maximum3_f32 v0, v32, v33, v33
	v_maximum3_f32 v0, v0, v34, v35
	v_maximum3_f32 v0, v0, v36, v37
	v_maximum3_f32 v0, v0, v38, v39
	v_maximum3_f32 v0, v0, v40, v41
	v_maximum3_f32 v0, v0, v42, v43
	v_maximum3_f32 v0, v0, v44, v45
	v_maximum3_f32 v0, v0, v46, v47
	v_mov_b32_e32 v1, v0
	s_nop 1
	v_permlane32_swap_b32_e32 v0, v1
	v_maximum3_f32 v0, v0, v1, v1
	v_sub_f32_e32 v0, v0, v64
	v_cmp_lt_f32_e32 vcc, s76, v0
	s_cbranch_vccz .LBB0_130
	v_max_f32_e32 v0, v0, v0
	v_max_f32_e32 v1, 0, v0
	v_exp_f32_e64 v0, -v1
	v_add_f32_e32 v64, v64, v1
	s_mov_b64 s[40:41], 0
	v_mul_f32_e32 v220, v220, v0
	v_pk_mul_f32 v[128:129], v[128:129], v[0:1] op_sel_hi:[1,0]
	v_pk_mul_f32 v[126:127], v[126:127], v[0:1] op_sel_hi:[1,0]
	v_pk_mul_f32 v[124:125], v[124:125], v[0:1] op_sel_hi:[1,0]
	v_pk_mul_f32 v[122:123], v[122:123], v[0:1] op_sel_hi:[1,0]
	v_pk_mul_f32 v[120:121], v[120:121], v[0:1] op_sel_hi:[1,0]
	v_pk_mul_f32 v[118:119], v[118:119], v[0:1] op_sel_hi:[1,0]
	v_pk_mul_f32 v[116:117], v[116:117], v[0:1] op_sel_hi:[1,0]
	v_pk_mul_f32 v[114:115], v[114:115], v[0:1] op_sel_hi:[1,0]
	v_pk_mul_f32 v[112:113], v[112:113], v[0:1] op_sel_hi:[1,0]
	v_pk_mul_f32 v[110:111], v[110:111], v[0:1] op_sel_hi:[1,0]
	v_pk_mul_f32 v[108:109], v[108:109], v[0:1] op_sel_hi:[1,0]
	v_pk_mul_f32 v[106:107], v[106:107], v[0:1] op_sel_hi:[1,0]
	v_pk_mul_f32 v[104:105], v[104:105], v[0:1] op_sel_hi:[1,0]
	v_pk_mul_f32 v[102:103], v[102:103], v[0:1] op_sel_hi:[1,0]
	v_pk_mul_f32 v[100:101], v[100:101], v[0:1] op_sel_hi:[1,0]
	v_pk_mul_f32 v[98:99], v[98:99], v[0:1] op_sel_hi:[1,0]

; DI float fexp2(float x) { return __builtin_amdgcn_exp2f(x); }
; DI void attn_core2(const u16* __restrict__ P, size_t tokbase, int kcol, int vcol, int n1, int n2, int xs0, bool win, int tq0,
;                    float m0, float l0, const bf16x8 (&qreg)[2][4], f32x16 (&o)[2][2], float (&lsum)[2], char* lds) {
;     ...
;       f32x16 pt[2]; pt[0] = fzero(); pt[1] = fzero();
; #pragma unroll
;       for (int s = 0; s < 4; ++s) {
;         const int ch = 2 * s + h, key = 32 * ks + r;
;         const bf16x8 kf = *(const bf16x8*)(base + ch * 1024 + ((key ^ ch) * 16));
;         pt[0] = MFMA(kf, qreg[0][s], pt[0]);
;         pt[1] = MFMA(kf, qreg[1][s], pt[1]);
;       }
; #pragma unroll
;       for (int qs = 0; qs < 2; ++qs) {
;         if (domask) {
; #pragma unroll
;           for (int reg = 0; reg < 16; ++reg) {
;             const int d = tq0 + 32 * qs - (kt0 + 32 * ks + crow(reg, h));
;             if (d > 128 || d < -128) pt[qs][reg] = -1e30f;
;           }
;         }
;         float mloc = mx2(pt[qs][0], pt[qs][1]);
; #pragma unroll
;         for (int reg = 2; reg < 16; reg += 2) mloc = mx2(mx2(mloc, pt[qs][reg]), pt[qs][reg + 1]);
;         mloc = hmax(mloc) - m[qs];
;         if (__builtin_amdgcn_ballot_w64(mloc > THR) != 0) {
;           const float d = fmaxf(mloc, 0.f);
;           const float alpha = fexp2(-d);
;           m[qs] += d; l[qs] *= alpha; mz[qs] = false;
; #pragma unroll
;           for (int b = 0; b < 2; ++b)
; #pragma unroll
;             for (int reg = 0; reg < 16; ++reg) o[qs][b][reg] *= alpha;
;         }
;         float la = 0.f;
;         if (mz[qs]) {
; #pragma unroll
;           for (int reg = 0; reg < 16; ++reg) { const float e = fexp2(pt[qs][reg]); pt[qs][reg] = e; la += e; }
;         } else {
; #pragma unroll
;           for (int reg = 0; reg < 16; ++reg) { const float e = fexp2(pt[qs][reg] - m[qs]); pt[qs][reg] = e; la += e; }
;         }
;         l[qs] += la;
;       }
; #pragma unroll
;       for (int s2 = 0; s2 < 2; ++s2) {
;         const bf16x8 pb0 = pack8(pt[0], s2), pb1 = pack8(pt[1], s2);
;         const int s16 = 2 * ks + s2;
; #pragma unroll
;         for (int b = 0; b < 2; ++b) {
;           const char* va = base + KB + b * 4096 + s16 * 1024 + trofs;
;           const bf16x8 vf = cat8(vtr(va), vtr(va + 512));
;           o[0][b] = MFMA(vf, pb0, o[0][b]);
;           o[1][b] = MFMA(vf, pb1, o[1][b]);
;         }
;       }
.LBB0_140:
	ds_read_b64_tr_b16 v[8:9], v185 offset:8192
	ds_read_b64_tr_b16 v[10:11], v185 offset:8704
	ds_read_b64_tr_b16 v[16:17], v185 offset:12288
	ds_read_b64_tr_b16 v[18:19], v185 offset:12800
	ds_read_b64_tr_b16 v[20:21], v185 offset:9216
	ds_read_b64_tr_b16 v[22:23], v185 offset:9728
	ds_read_b64_tr_b16 v[24:25], v185 offset:13312
	ds_read_b64_tr_b16 v[26:27], v185 offset:13824
	ds_read_b128 v[226:229], v215
	ds_read_b128 v[238:241], v216
	ds_read_b128 v[242:245], v217
	ds_read_b128 v[246:249], v218
	v_add_f32_e32 v0, v15, v222
	v_add_f32_e32 v220, v220, v0
	v_cvt_pk_bf16_f32 v0, v32, v33
	v_cvt_pk_bf16_f32 v1, v34, v35
	v_cvt_pk_bf16_f32 v2, v36, v37
	v_cvt_pk_bf16_f32 v3, v38, v39
	v_cvt_pk_bf16_f32 v4, v48, v49
	v_cvt_pk_bf16_f32 v5, v50, v51
	v_cvt_pk_bf16_f32 v6, v52, v53
	v_cvt_pk_bf16_f32 v7, v54, v55
	s_waitcnt lgkmcnt(10)
	v_mfma_f32_32x32x16_bf16 v[114:129], v[8:11], v[0:3], v[114:129]
	v_exp_f32_e32 v15, v223
	v_mfma_f32_32x32x16_bf16 v[82:97], v[8:11], v[4:7], v[82:97]
	s_waitcnt lgkmcnt(8)
	v_mfma_f32_32x32x16_bf16 v[98:113], v[16:19], v[0:3], v[98:113]
	v_cvt_pk_bf16_f32 v0, v40, v41
	v_cvt_pk_bf16_f32 v1, v42, v43
	v_cvt_pk_bf16_f32 v2, v44, v45
	v_cvt_pk_bf16_f32 v3, v46, v47
	v_mfma_f32_32x32x16_bf16 v[66:81], v[16:19], v[4:7], v[66:81]
	v_cvt_pk_bf16_f32 v4, v56, v57
	v_cvt_pk_bf16_f32 v5, v58, v59
	v_cvt_pk_bf16_f32 v6, v60, v61
	v_cvt_pk_bf16_f32 v7, v62, v15
	s_waitcnt lgkmcnt(6)
	v_mfma_f32_32x32x16_bf16 v[114:129], v[20:23], v[0:3], v[114:129]
	v_mfma_f32_32x32x16_bf16 v[82:97], v[20:23], v[4:7], v[82:97]
	s_waitcnt lgkmcnt(4)
	v_mfma_f32_32x32x16_bf16 v[98:113], v[24:27], v[0:3], v[98:113]
	v_mfma_f32_32x32x16_bf16 v[66:81], v[24:27], v[4:7], v[66:81]
	s_waitcnt lgkmcnt(3)
	v_mfma_f32_32x32x16_bf16 v[32:47], v[226:229], v[130:133], 0
	v_mfma_f32_32x32x16_bf16 v[16:31], v[226:229], v[146:149], 0
	s_waitcnt lgkmcnt(2)
	v_mfma_f32_32x32x16_bf16 v[32:47], v[238:241], v[134:137], v[32:47]
	v_mfma_f32_32x32x16_bf16 v[16:31], v[238:241], v[150:153], v[16:31]
	s_waitcnt lgkmcnt(1)
	v_mfma_f32_32x32x16_bf16 v[32:47], v[242:245], v[138:141], v[32:47]
	v_mfma_f32_32x32x16_bf16 v[16:31], v[242:245], v[154:157], v[16:31]
	s_waitcnt lgkmcnt(0)
	v_mfma_f32_32x32x16_bf16 v[32:47], v[246:249], v[142:145], v[32:47]
	v_mfma_f32_32x32x16_bf16 v[16:31], v[246:249], v[158:161], v[16:31]
	s_nop 10
	v_maximum3_f32 v0, v32, v33, v33
	v_maximum3_f32 v0, v0, v34, v35
	v_maximum3_f32 v0, v0, v36, v37
	v_maximum3_f32 v0, v0, v38, v39
	v_maximum3_f32 v0, v0, v40, v41
	v_maximum3_f32 v0, v0, v42, v43
	v_maximum3_f32 v0, v0, v44, v45
	v_maximum3_f32 v0, v0, v46, v47
	v_mov_b32_e32 v1, v0
	s_nop 1
	v_permlane32_swap_b32_e32 v0, v1
	v_maximum3_f32 v0, v0, v1, v1
	v_sub_f32_e32 v0, v0, v64
	v_cmp_lt_f32_e32 vcc, s76, v0
	s_cbranch_vccz .LBB0_142
	v_max_f32_e32 v0, v0, v0
	v_max_f32_e32 v1, 0, v0
	v_exp_f32_e64 v0, -v1
	v_add_f32_e32 v64, v64, v1
	s_mov_b64 s[40:41], 0
	v_mul_f32_e32 v220, v220, v0
	v_pk_mul_f32 v[128:129], v[128:129], v[0:1] op_sel_hi:[1,0]
	v_pk_mul_f32 v[126:127], v[126:127], v[0:1] op_sel_hi:[1,0]
	v_pk_mul_f32 v[124:125], v[124:125], v[0:1] op_sel_hi:[1,0]
	v_pk_mul_f32 v[122:123], v[122:123], v[0:1] op_sel_hi:[1,0]
	v_pk_mul_f32 v[120:121], v[120:121], v[0:1] op_sel_hi:[1,0]
	v_pk_mul_f32 v[118:119], v[118:119], v[0:1] op_sel_hi:[1,0]
	v_pk_mul_f32 v[116:117], v[116:117], v[0:1] op_sel_hi:[1,0]
	v_pk_mul_f32 v[114:115], v[114:115], v[0:1] op_sel_hi:[1,0]
	v_pk_mul_f32 v[112:113], v[112:113], v[0:1] op_sel_hi:[1,0]
	v_pk_mul_f32 v[110:111], v[110:111], v[0:1] op_sel_hi:[1,0]
	v_pk_mul_f32 v[108:109], v[108:109], v[0:1] op_sel_hi:[1,0]
	v_pk_mul_f32 v[106:107], v[106:107], v[0:1] op_sel_hi:[1,0]
	v_pk_mul_f32 v[104:105], v[104:105], v[0:1] op_sel_hi:[1,0]
	v_pk_mul_f32 v[102:103], v[102:103], v[0:1] op_sel_hi:[1,0]
	v_pk_mul_f32 v[100:101], v[100:101], v[0:1] op_sel_hi:[1,0]
	v_pk_mul_f32 v[98:99], v[98:99], v[0:1] op_sel_hi:[1,0]

; DI void attn_core2(const u16* __restrict__ P, size_t tokbase, int kcol, int vcol, int n1, int n2, int xs0, bool win, int tq0,
;                    float m0, float l0, const bf16x8 (&qreg)[2][4], f32x16 (&o)[2][2], float (&lsum)[2], char* lds) {
;     ...
;       f32x16 pt[2]; pt[0] = fzero(); pt[1] = fzero();
; #pragma unroll
;       for (int s = 0; s < 4; ++s) {
;         const int ch = 2 * s + h, key = 32 * ks + r;
;         const bf16x8 kf = *(const bf16x8*)(base + ch * 1024 + ((key ^ ch) * 16));
;         pt[0] = MFMA(kf, qreg[0][s], pt[0]);
;         pt[1] = MFMA(kf, qreg[1][s], pt[1]);
;       }
; #pragma unroll
;       for (int qs = 0; qs < 2; ++qs) {
;         if (domask) {
; #pragma unroll
;           for (int reg = 0; reg < 16; ++reg) {
;             const int d = tq0 + 32 * qs - (kt0 + 32 * ks + crow(reg, h));
;             if (d > 128 || d < -128) pt[qs][reg] = -1e30f;
;           }
;         }
;         float mloc = mx2(pt[qs][0], pt[qs][1]);
; #pragma unroll
;         for (int reg = 2; reg < 16; reg += 2) mloc = mx2(mx2(mloc, pt[qs][reg]), pt[qs][reg + 1]);
;         mloc = hmax(mloc) - m[qs];
;         if (__builtin_amdgcn_ballot_w64(mloc > THR) != 0) {
;           const float d = fmaxf(mloc, 0.f);
;           const float alpha = fexp2(-d);
;           m[qs] += d; l[qs] *= alpha; mz[qs] = false;
; #pragma unroll
;           for (int b = 0; b < 2; ++b)
; #pragma unroll
;             for (int reg = 0; reg < 16; ++reg) o[qs][b][reg] *= alpha;
;         }
;         float la = 0.f;
;         if (mz[qs]) {
; #pragma unroll
;           for (int reg = 0; reg < 16; ++reg) { const float e = fexp2(pt[qs][reg]); pt[qs][reg] = e; la += e; }
;         } else {
; #pragma unroll
;           for (int reg = 0; reg < 16; ++reg) { const float e = fexp2(pt[qs][reg] - m[qs]); pt[qs][reg] = e; la += e; }
;         }
;         l[qs] += la;
;       }
; #pragma unroll
;       for (int s2 = 0; s2 < 2; ++s2) {
;         const bf16x8 pb0 = pack8(pt[0], s2), pb1 = pack8(pt[1], s2);
;         const int s16 = 2 * ks + s2;
; #pragma unroll
;         for (int b = 0; b < 2; ++b) {
;           const char* va = base + KB + b * 4096 + s16 * 1024 + trofs;
;           const bf16x8 vf = cat8(vtr(va), vtr(va + 512));
;           o[0][b] = MFMA(vf, pb0, o[0][b]);
;           o[1][b] = MFMA(vf, pb1, o[1][b]);
;         }
;       }
;     ...
;     A_LOAD(kA, vA, it + 1);
;     compute(lds, it);
.LBB0_152:
	ds_read_b64_tr_b16 v[8:9], v185 offset:10240
	ds_read_b64_tr_b16 v[10:11], v185 offset:10752
	ds_read_b64_tr_b16 v[16:17], v185 offset:14336
	ds_read_b64_tr_b16 v[18:19], v185 offset:14848
	ds_read_b64_tr_b16 v[20:21], v185 offset:11264
	ds_read_b64_tr_b16 v[22:23], v185 offset:11776
	ds_read_b64_tr_b16 v[24:25], v185 offset:15360
	ds_read_b64_tr_b16 v[26:27], v185 offset:15872
	v_cvt_pk_bf16_f32 v0, v32, v33
	v_cvt_pk_bf16_f32 v1, v34, v35
	v_cvt_pk_bf16_f32 v2, v36, v37
	v_cvt_pk_bf16_f32 v3, v38, v39
	v_cvt_pk_bf16_f32 v4, v48, v49
	v_cvt_pk_bf16_f32 v5, v50, v51
	v_cvt_pk_bf16_f32 v6, v52, v53
	v_cvt_pk_bf16_f32 v7, v54, v55
	s_waitcnt lgkmcnt(6)
	v_mfma_f32_32x32x16_bf16 v[114:129], v[8:11], v[0:3], v[114:129]
	v_exp_f32_e32 v63, v219
	s_cmpk_lt_u32 s47, 0x42
	s_cselect_b64 s[44:45], -1, 0
	s_cmpk_gt_u32 s47, 0x41
	s_cselect_b64 s[42:43], -1, 0
	v_add_u32_e32 v219, v183, v184
	s_and_b64 vcc, exec, s[42:43]
	v_mfma_f32_32x32x16_bf16 v[82:97], v[8:11], v[4:7], v[82:97]
	s_waitcnt lgkmcnt(4)
	v_mfma_f32_32x32x16_bf16 v[98:113], v[16:19], v[0:3], v[98:113]
	v_cvt_pk_bf16_f32 v0, v40, v41
	v_cvt_pk_bf16_f32 v1, v42, v43
	v_cvt_pk_bf16_f32 v2, v44, v45
	v_cvt_pk_bf16_f32 v3, v46, v47
	v_mfma_f32_32x32x16_bf16 v[66:81], v[16:19], v[4:7], v[66:81]
	v_cvt_pk_bf16_f32 v4, v56, v57
	v_cvt_pk_bf16_f32 v5, v58, v59
	v_cvt_pk_bf16_f32 v6, v60, v61
	v_cvt_pk_bf16_f32 v7, v62, v63
	s_waitcnt lgkmcnt(2)
	v_mfma_f32_32x32x16_bf16 v[114:129], v[20:23], v[0:3], v[114:129]
	v_mfma_f32_32x32x16_bf16 v[82:97], v[20:23], v[4:7], v[82:97]
	s_waitcnt lgkmcnt(0)
	v_mfma_f32_32x32x16_bf16 v[98:113], v[24:27], v[0:3], v[98:113]
	v_mfma_f32_32x32x16_bf16 v[66:81], v[24:27], v[4:7], v[66:81]
	s_waitcnt vmcnt(3)
	ds_write_b128 v181, v[162:165] offset:16384
	s_waitcnt vmcnt(2)
	ds_write_b128 v182, v[170:173] offset:16384
	s_waitcnt vmcnt(1)
	ds_write_b128 v219, v[166:169] offset:24576
	s_waitcnt vmcnt(0)
	ds_write_b128 v219, v[174:177] offset:26624
	s_waitcnt lgkmcnt(0)
	s_barrier
	s_cbranch_vccnz .LBB0_154
	v_add_co_u32_e32 v0, vcc, 0xfffa4000, v178
	s_nop 1
	v_addc_co_u32_e32 v1, vcc, -1, v179, vcc
	global_load_dwordx4 v[162:165], v[0:1], off offset:-2560
	global_load_dwordx4 v[166:169], v[0:1], off offset:-2048
	global_load_dwordx4 v[170:173], v[178:179], off offset:-512
	global_load_dwordx4 v[174:177], v[178:179], off
.LBB0_154:
	v_add_f32_e32 v0, v15, v223
	v_add_f32_e32 v220, v220, v0
	ds_read_b128 v[226:229], v187 offset:16384
	ds_read_b128 v[238:241], v188 offset:16384
	ds_read_b128 v[242:245], v189 offset:16384
	ds_read_b128 v[246:249], v214 offset:16384
	s_waitcnt lgkmcnt(3)
	v_mfma_f32_32x32x16_bf16 v[32:47], v[226:229], v[130:133], 0
	v_mfma_f32_32x32x16_bf16 v[16:31], v[226:229], v[146:149], 0
	s_waitcnt lgkmcnt(2)
	v_mfma_f32_32x32x16_bf16 v[32:47], v[238:241], v[134:137], v[32:47]
	v_mfma_f32_32x32x16_bf16 v[16:31], v[238:241], v[150:153], v[16:31]
	s_waitcnt lgkmcnt(1)
	v_mfma_f32_32x32x16_bf16 v[32:47], v[242:245], v[138:141], v[32:47]
	v_mfma_f32_32x32x16_bf16 v[16:31], v[242:245], v[154:157], v[16:31]
	s_waitcnt lgkmcnt(0)
	v_mfma_f32_32x32x16_bf16 v[32:47], v[246:249], v[142:145], v[32:47]
	v_mfma_f32_32x32x16_bf16 v[16:31], v[246:249], v[158:161], v[16:31]
	s_nop 10
	v_maximum3_f32 v0, v32, v33, v33
	v_maximum3_f32 v0, v0, v34, v35
	v_maximum3_f32 v0, v0, v36, v37
	v_maximum3_f32 v0, v0, v38, v39
	v_maximum3_f32 v0, v0, v40, v41
	v_maximum3_f32 v0, v0, v42, v43
	v_maximum3_f32 v0, v0, v44, v45
	v_maximum3_f32 v0, v0, v46, v47
	v_mov_b32_e32 v1, v0
	s_nop 1
	v_permlane32_swap_b32_e32 v0, v1
	v_maximum3_f32 v0, v0, v1, v1
	v_sub_f32_e32 v0, v0, v64
	v_cmp_lt_f32_e32 vcc, s76, v0
	s_cbranch_vccz .LBB0_156
	v_max_f32_e32 v0, v0, v0
	v_max_f32_e32 v1, 0, v0
	v_exp_f32_e64 v0, -v1
	v_add_f32_e32 v64, v64, v1
	s_mov_b64 s[40:41], 0
	v_mul_f32_e32 v220, v220, v0
	v_pk_mul_f32 v[128:129], v[128:129], v[0:1] op_sel_hi:[1,0]
	v_pk_mul_f32 v[126:127], v[126:127], v[0:1] op_sel_hi:[1,0]
	v_pk_mul_f32 v[124:125], v[124:125], v[0:1] op_sel_hi:[1,0]
	v_pk_mul_f32 v[122:123], v[122:123], v[0:1] op_sel_hi:[1,0]
	v_pk_mul_f32 v[120:121], v[120:121], v[0:1] op_sel_hi:[1,0]
	v_pk_mul_f32 v[118:119], v[118:119], v[0:1] op_sel_hi:[1,0]
	v_pk_mul_f32 v[116:117], v[116:117], v[0:1] op_sel_hi:[1,0]
	v_pk_mul_f32 v[114:115], v[114:115], v[0:1] op_sel_hi:[1,0]
	v_pk_mul_f32 v[112:113], v[112:113], v[0:1] op_sel_hi:[1,0]
	v_pk_mul_f32 v[110:111], v[110:111], v[0:1] op_sel_hi:[1,0]
	v_pk_mul_f32 v[108:109], v[108:109], v[0:1] op_sel_hi:[1,0]
	v_pk_mul_f32 v[106:107], v[106:107], v[0:1] op_sel_hi:[1,0]
	v_pk_mul_f32 v[104:105], v[104:105], v[0:1] op_sel_hi:[1,0]
	v_pk_mul_f32 v[102:103], v[102:103], v[0:1] op_sel_hi:[1,0]
	v_pk_mul_f32 v[100:101], v[100:101], v[0:1] op_sel_hi:[1,0]
	v_pk_mul_f32 v[98:99], v[98:99], v[0:1] op_sel_hi:[1,0]

; DI float fexp2(float x) { return __builtin_amdgcn_exp2f(x); }
; DI void attn_core2(const u16* __restrict__ P, size_t tokbase, int kcol, int vcol, int n1, int n2, int xs0, bool win, int tq0,
;                    float m0, float l0, const bf16x8 (&qreg)[2][4], f32x16 (&o)[2][2], float (&lsum)[2], char* lds) {
;     ...
;       f32x16 pt[2]; pt[0] = fzero(); pt[1] = fzero();
; #pragma unroll
;       for (int s = 0; s < 4; ++s) {
;         const int ch = 2 * s + h, key = 32 * ks + r;
;         const bf16x8 kf = *(const bf16x8*)(base + ch * 1024 + ((key ^ ch) * 16));
;         pt[0] = MFMA(kf, qreg[0][s], pt[0]);
;         pt[1] = MFMA(kf, qreg[1][s], pt[1]);
;       }
; #pragma unroll
;       for (int qs = 0; qs < 2; ++qs) {
;         if (domask) {
; #pragma unroll
;           for (int reg = 0; reg < 16; ++reg) {
;             const int d = tq0 + 32 * qs - (kt0 + 32 * ks + crow(reg, h));
;             if (d > 128 || d < -128) pt[qs][reg] = -1e30f;
;           }
;         }
;         float mloc = mx2(pt[qs][0], pt[qs][1]);
; #pragma unroll
;         for (int reg = 2; reg < 16; reg += 2) mloc = mx2(mx2(mloc, pt[qs][reg]), pt[qs][reg + 1]);
;         mloc = hmax(mloc) - m[qs];
;         if (__builtin_amdgcn_ballot_w64(mloc > THR) != 0) {
;           const float d = fmaxf(mloc, 0.f);
;           const float alpha = fexp2(-d);
;           m[qs] += d; l[qs] *= alpha; mz[qs] = false;
; #pragma unroll
;           for (int b = 0; b < 2; ++b)
; #pragma unroll
;             for (int reg = 0; reg < 16; ++reg) o[qs][b][reg] *= alpha;
;         }
;         float la = 0.f;
;         if (mz[qs]) {
; #pragma unroll
;           for (int reg = 0; reg < 16; ++reg) { const float e = fexp2(pt[qs][reg]); pt[qs][reg] = e; la += e; }
;         } else {
; #pragma unroll
;           for (int reg = 0; reg < 16; ++reg) { const float e = fexp2(pt[qs][reg] - m[qs]); pt[qs][reg] = e; la += e; }
;         }
;         l[qs] += la;
;       }
; #pragma unroll
;       for (int s2 = 0; s2 < 2; ++s2) {
;         const bf16x8 pb0 = pack8(pt[0], s2), pb1 = pack8(pt[1], s2);
;         const int s16 = 2 * ks + s2;
; #pragma unroll
;         for (int b = 0; b < 2; ++b) {
;           const char* va = base + KB + b * 4096 + s16 * 1024 + trofs;
;           const bf16x8 vf = cat8(vtr(va), vtr(va + 512));
;           o[0][b] = MFMA(vf, pb0, o[0][b]);
;           o[1][b] = MFMA(vf, pb1, o[1][b]);
;         }
;       }
.LBB0_166:
	ds_read_b64_tr_b16 v[8:9], v185 offset:24576
	ds_read_b64_tr_b16 v[10:11], v185 offset:25088
	ds_read_b64_tr_b16 v[16:17], v185 offset:28672
	ds_read_b64_tr_b16 v[18:19], v185 offset:29184
	ds_read_b64_tr_b16 v[20:21], v185 offset:25600
	ds_read_b64_tr_b16 v[22:23], v185 offset:26112
	ds_read_b64_tr_b16 v[24:25], v185 offset:29696
	ds_read_b64_tr_b16 v[26:27], v185 offset:30208
	ds_read_b128 v[226:229], v215 offset:16384
	ds_read_b128 v[238:241], v216 offset:16384
	ds_read_b128 v[242:245], v217 offset:16384
	ds_read_b128 v[246:249], v218 offset:16384
	v_add_f32_e32 v0, v15, v223
	v_add_f32_e32 v220, v220, v0
	v_cvt_pk_bf16_f32 v0, v32, v33
	v_cvt_pk_bf16_f32 v1, v34, v35
	v_cvt_pk_bf16_f32 v2, v36, v37
	v_cvt_pk_bf16_f32 v3, v38, v39
	v_cvt_pk_bf16_f32 v4, v48, v49
	v_cvt_pk_bf16_f32 v5, v50, v51
	v_cvt_pk_bf16_f32 v6, v52, v53
	v_cvt_pk_bf16_f32 v7, v54, v55
	s_waitcnt lgkmcnt(10)
	v_mfma_f32_32x32x16_bf16 v[114:129], v[8:11], v[0:3], v[114:129]
	v_exp_f32_e32 v15, v224
	v_mfma_f32_32x32x16_bf16 v[82:97], v[8:11], v[4:7], v[82:97]
	s_waitcnt lgkmcnt(8)
	v_mfma_f32_32x32x16_bf16 v[98:113], v[16:19], v[0:3], v[98:113]
	v_cvt_pk_bf16_f32 v0, v40, v41
	v_cvt_pk_bf16_f32 v1, v42, v43
	v_cvt_pk_bf16_f32 v2, v44, v45
	v_cvt_pk_bf16_f32 v3, v46, v47
	v_mfma_f32_32x32x16_bf16 v[66:81], v[16:19], v[4:7], v[66:81]
	v_cvt_pk_bf16_f32 v4, v56, v57
	v_cvt_pk_bf16_f32 v5, v58, v59
	v_cvt_pk_bf16_f32 v6, v60, v61
	v_cvt_pk_bf16_f32 v7, v62, v15
	s_waitcnt lgkmcnt(6)
	v_mfma_f32_32x32x16_bf16 v[114:129], v[20:23], v[0:3], v[114:129]
	v_mfma_f32_32x32x16_bf16 v[82:97], v[20:23], v[4:7], v[82:97]
	s_waitcnt lgkmcnt(4)
	v_mfma_f32_32x32x16_bf16 v[98:113], v[24:27], v[0:3], v[98:113]
	v_mfma_f32_32x32x16_bf16 v[66:81], v[24:27], v[4:7], v[66:81]
	s_waitcnt lgkmcnt(3)
	v_mfma_f32_32x32x16_bf16 v[32:47], v[226:229], v[130:133], 0
	v_mfma_f32_32x32x16_bf16 v[16:31], v[226:229], v[146:149], 0
	s_waitcnt lgkmcnt(2)
	v_mfma_f32_32x32x16_bf16 v[32:47], v[238:241], v[134:137], v[32:47]
	v_mfma_f32_32x32x16_bf16 v[16:31], v[238:241], v[150:153], v[16:31]
	s_waitcnt lgkmcnt(1)
	v_mfma_f32_32x32x16_bf16 v[32:47], v[242:245], v[138:141], v[32:47]
	v_mfma_f32_32x32x16_bf16 v[16:31], v[242:245], v[154:157], v[16:31]
	s_waitcnt lgkmcnt(0)
	v_mfma_f32_32x32x16_bf16 v[32:47], v[246:249], v[142:145], v[32:47]
	v_mfma_f32_32x32x16_bf16 v[16:31], v[246:249], v[158:161], v[16:31]
	s_nop 10
	v_maximum3_f32 v0, v32, v33, v33
	v_maximum3_f32 v0, v0, v34, v35
	v_maximum3_f32 v0, v0, v36, v37
	v_maximum3_f32 v0, v0, v38, v39
	v_maximum3_f32 v0, v0, v40, v41
	v_maximum3_f32 v0, v0, v42, v43
	v_maximum3_f32 v0, v0, v44, v45
	v_maximum3_f32 v0, v0, v46, v47
	v_mov_b32_e32 v1, v0
	s_nop 1
	v_permlane32_swap_b32_e32 v0, v1
	v_maximum3_f32 v0, v0, v1, v1
	v_sub_f32_e32 v0, v0, v64
	v_cmp_lt_f32_e32 vcc, s76, v0
	s_cbranch_vccz .LBB0_168
	v_max_f32_e32 v0, v0, v0
	v_max_f32_e32 v1, 0, v0
	v_exp_f32_e64 v0, -v1
	v_add_f32_e32 v64, v64, v1
	s_mov_b64 s[40:41], 0
	v_mul_f32_e32 v220, v220, v0
	v_pk_mul_f32 v[128:129], v[128:129], v[0:1] op_sel_hi:[1,0]
	v_pk_mul_f32 v[126:127], v[126:127], v[0:1] op_sel_hi:[1,0]
	v_pk_mul_f32 v[124:125], v[124:125], v[0:1] op_sel_hi:[1,0]
	v_pk_mul_f32 v[122:123], v[122:123], v[0:1] op_sel_hi:[1,0]
	v_pk_mul_f32 v[120:121], v[120:121], v[0:1] op_sel_hi:[1,0]
	v_pk_mul_f32 v[118:119], v[118:119], v[0:1] op_sel_hi:[1,0]
	v_pk_mul_f32 v[116:117], v[116:117], v[0:1] op_sel_hi:[1,0]
	v_pk_mul_f32 v[114:115], v[114:115], v[0:1] op_sel_hi:[1,0]
	v_pk_mul_f32 v[112:113], v[112:113], v[0:1] op_sel_hi:[1,0]
	v_pk_mul_f32 v[110:111], v[110:111], v[0:1] op_sel_hi:[1,0]
	v_pk_mul_f32 v[108:109], v[108:109], v[0:1] op_sel_hi:[1,0]
	v_pk_mul_f32 v[106:107], v[106:107], v[0:1] op_sel_hi:[1,0]
	v_pk_mul_f32 v[104:105], v[104:105], v[0:1] op_sel_hi:[1,0]
	v_pk_mul_f32 v[102:103], v[102:103], v[0:1] op_sel_hi:[1,0]
	v_pk_mul_f32 v[100:101], v[100:101], v[0:1] op_sel_hi:[1,0]
	v_pk_mul_f32 v[98:99], v[98:99], v[0:1] op_sel_hi:[1,0]

; #define MFMA(a, b, c) __builtin_amdgcn_mfma_f32_32x32x16_bf16((a), (b), (c), 0, 0, 0)
; DI s16x4 vtr(const char* p) { return __builtin_bit_cast(s16x4, __builtin_amdgcn_ds_read_tr16_b64_v4i16((__attribute__((address_space(3))) v4i16_t*)(lds_cptr)p)); }
; DI bf16x8 cat8(s16x4 lo, s16x4 hi) { return __builtin_shufflevector(lo, hi, 0, 1, 2, 3, 4, 5, 6, 7); }
; DI void attn_core2(const u16* __restrict__ P, size_t tokbase, int kcol, int vcol, int n1, int n2, int xs0, bool win, int tq0,
;                    float m0, float l0, const bf16x8 (&qreg)[2][4], f32x16 (&o)[2][2], float (&lsum)[2], char* lds) {
;     ...
; #pragma unroll
;       for (int s2 = 0; s2 < 2; ++s2) {
;         const bf16x8 pb0 = pack8(pt[0], s2), pb1 = pack8(pt[1], s2);
;         const int s16 = 2 * ks + s2;
; #pragma unroll
;         for (int b = 0; b < 2; ++b) {
;           const char* va = base + KB + b * 4096 + s16 * 1024 + trofs;
;           const bf16x8 vf = cat8(vtr(va), vtr(va + 512));
;           o[0][b] = MFMA(vf, pb0, o[0][b]);
;           o[1][b] = MFMA(vf, pb1, o[1][b]);
;         }
;       }
;     ...
;     A_STORE(kA, vA, 1);
;     __syncthreads();
;     if (it + 2 < ntiles) A_LOAD(kA, vA, it + 2);
;     compute(lds + STAGE, it + 1);
;     if (it + 2 < ntiles) A_STORE(kA, vA, 0);
;     __syncthreads();
.LBB0_178:
	ds_read_b64_tr_b16 v[10:11], v185 offset:26624
	ds_read_b64_tr_b16 v[12:13], v185 offset:27136
	ds_read_b64_tr_b16 v[16:17], v185 offset:30720
	ds_read_b64_tr_b16 v[18:19], v185 offset:31232
	ds_read_b64_tr_b16 v[20:21], v185 offset:27648
	ds_read_b64_tr_b16 v[22:23], v185 offset:28160
	ds_read_b64_tr_b16 v[24:25], v185 offset:31744
	ds_read_b64_tr_b16 v[26:27], v185 offset:32256
	v_cvt_pk_bf16_f32 v2, v32, v33
	v_cvt_pk_bf16_f32 v3, v34, v35
	v_cvt_pk_bf16_f32 v4, v36, v37
	v_cvt_pk_bf16_f32 v5, v38, v39
	v_cvt_pk_bf16_f32 v6, v48, v49
	v_cvt_pk_bf16_f32 v7, v50, v51
	v_cvt_pk_bf16_f32 v8, v52, v53
	v_cvt_pk_bf16_f32 v9, v54, v55
	s_waitcnt lgkmcnt(6)
	v_mfma_f32_32x32x16_bf16 v[114:129], v[10:13], v[2:5], v[114:129]
	v_exp_f32_e32 v0, v224
	s_andn2_b64 vcc, exec, s[44:45]
	v_mfma_f32_32x32x16_bf16 v[82:97], v[10:13], v[6:9], v[82:97]
	s_waitcnt lgkmcnt(4)
	v_mfma_f32_32x32x16_bf16 v[98:113], v[16:19], v[2:5], v[98:113]
	v_cvt_pk_bf16_f32 v2, v40, v41
	v_cvt_pk_bf16_f32 v3, v42, v43
	v_cvt_pk_bf16_f32 v4, v44, v45
	v_cvt_pk_bf16_f32 v5, v46, v47
	v_mfma_f32_32x32x16_bf16 v[66:81], v[16:19], v[6:9], v[66:81]
	v_cvt_pk_bf16_f32 v6, v56, v57
	v_cvt_pk_bf16_f32 v7, v58, v59
	v_cvt_pk_bf16_f32 v8, v60, v61
	v_cvt_pk_bf16_f32 v9, v62, v0
	s_waitcnt lgkmcnt(2)
	v_mfma_f32_32x32x16_bf16 v[114:129], v[20:23], v[2:5], v[114:129]
	v_mfma_f32_32x32x16_bf16 v[82:97], v[20:23], v[6:9], v[82:97]
	s_waitcnt lgkmcnt(0)
	v_mfma_f32_32x32x16_bf16 v[98:113], v[24:27], v[2:5], v[98:113]
	v_mfma_f32_32x32x16_bf16 v[66:81], v[24:27], v[6:9], v[66:81]
	s_cbranch_vccnz .LBB0_127
	s_waitcnt vmcnt(3)
	ds_write_b128 v181, v[162:165]
	s_waitcnt vmcnt(1)
	ds_write_b128 v182, v[170:173]
	ds_write_b128 v219, v[166:169] offset:8192
	s_waitcnt vmcnt(0)
	ds_write_b128 v219, v[174:177] offset:10240
	s_branch .LBB0_127
